# top-k bit 31/1/0 and final steps also use scalar compare (s_cmp_gt_u32) instead of v_cmp_gt_u64 + s_and exec
# baseline (speedup 1.0000x reference)
.LBB0_799:
	v_add_u32_e32 v1, 0, v0
	v_add_u32_e32 v4, 0x4000, v1
	ds_read2_b32 v[2:3], v1 offset1:65
	ds_read2_b32 v[4:5], v4 offset0:64 offset1:129
	ds_read2_b32 v[10:11], v1 offset0:130 offset1:195
	v_add_u32_e32 v1, 0x4200, v1
	ds_read2_b32 v[12:13], v1 offset0:66 offset1:131
	s_waitcnt lgkmcnt(2)
	v_add_f32_e32 v2, v2, v4
	v_cndmask_b32_e64 v2, v2, v233, s[0:1]
	v_cndmask_b32_e32 v7, v2, v234, vcc
	v_add_f32_e32 v3, v3, v5
	v_not_b32_e32 v2, v7
	v_or_b32_e32 v4, 0x80000000, v7
	v_cmp_gt_i32_e64 s[8:9], 0, v7
	s_nop 1
	v_cndmask_b32_e64 v8, v4, v2, s[8:9]
	v_cndmask_b32_e64 v2, v3, v233, s[0:1]
	v_cndmask_b32_e32 v5, v2, v234, vcc
	v_not_b32_e32 v1, v5
	v_or_b32_e32 v2, 0x80000000, v5
	v_cmp_gt_i32_e64 s[8:9], 0, v5
	s_nop 1
	v_cndmask_b32_e64 v6, v2, v1, s[8:9]
	s_waitcnt lgkmcnt(0)
	v_add_f32_e32 v1, v10, v12
	v_cndmask_b32_e64 v1, v1, v233, s[0:1]
	v_cndmask_b32_e32 v3, v1, v234, vcc
	v_not_b32_e32 v1, v3
	v_or_b32_e32 v2, 0x80000000, v3
	v_cmp_gt_i32_e64 s[8:9], 0, v3
	s_nop 1
	v_cndmask_b32_e64 v4, v2, v1, s[8:9]
	v_add_f32_e32 v1, v11, v13
	v_cndmask_b32_e64 v1, v1, v233, s[0:1]
	v_cndmask_b32_e32 v1, v1, v234, vcc
	v_not_b32_e32 v2, v1
	v_or_b32_e32 v9, 0x80000000, v1
	v_cmp_gt_i32_e64 s[8:9], 0, v1
	s_nop 1
	v_cndmask_b32_e64 v2, v9, v2, s[8:9]
	v_cmp_gt_i32_e64 s[8:9], 0, v8
	s_bcnt1_i32_b64 s62, s[8:9]
	s_cmp_gt_u32 s62, 15
	s_nop 0
	v_cmp_gt_i32_e64 s[8:9], 0, v6
	s_cselect_b32 s12, 0x80000000, 0
	s_bcnt1_i32_b64 s62, s[8:9]
	s_cmp_gt_u32 s62, 15
	s_nop 0
	v_cmp_gt_i32_e64 s[8:9], 0, v4
	s_cselect_b32 s13, 0x80000000, 0
	s_bcnt1_i32_b64 s62, s[8:9]
	s_cmp_gt_u32 s62, 15
	s_nop 0
	v_cmp_gt_i32_e64 s[8:9], 0, v2
	s_cselect_b32 s14, 0x80000000, 0
	s_bcnt1_i32_b64 s62, s[8:9]
	s_cmp_gt_u32 s62, 15
	s_nop 0
	s_cselect_b32 s15, 0x80000000, 0
	s_or_b32 s16, s12, 0x40000000
	s_or_b32 s95, s13, 0x40000000
	v_cmp_le_u32_e64 s[8:9], s16, v8
	v_cmp_le_u32_e64 s[2:3], s95, v6
	s_bcnt1_i32_b64 s62, s[8:9]
	s_bcnt1_i32_b64 s97, s[2:3]
	s_cmp_gt_u32 s62, 15
	s_cselect_b32 s12, s16, s12
	s_cmp_gt_u32 s97, 15
	s_cselect_b32 s13, s95, s13
	s_or_b32 s16, s14, 0x40000000
	s_or_b32 s95, s15, 0x40000000
	v_cmp_le_u32_e64 s[8:9], s16, v4
	v_cmp_le_u32_e64 s[2:3], s95, v2
	s_bcnt1_i32_b64 s62, s[8:9]
	s_bcnt1_i32_b64 s97, s[2:3]
	s_cmp_gt_u32 s62, 15
	s_cselect_b32 s14, s16, s14
	s_cmp_gt_u32 s97, 15
	s_cselect_b32 s15, s95, s15
	s_or_b32 s16, s12, 0x20000000
	s_or_b32 s95, s13, 0x20000000
	v_cmp_le_u32_e64 s[8:9], s16, v8
	v_cmp_le_u32_e64 s[2:3], s95, v6
	s_bcnt1_i32_b64 s62, s[8:9]
	s_bcnt1_i32_b64 s97, s[2:3]
	s_cmp_gt_u32 s62, 15
	s_cselect_b32 s12, s16, s12
	s_cmp_gt_u32 s97, 15
	s_cselect_b32 s13, s95, s13
	s_or_b32 s16, s14, 0x20000000
	s_or_b32 s95, s15, 0x20000000
	v_cmp_le_u32_e64 s[8:9], s16, v4
	v_cmp_le_u32_e64 s[2:3], s95, v2
	s_bcnt1_i32_b64 s62, s[8:9]
	s_bcnt1_i32_b64 s97, s[2:3]
	s_cmp_gt_u32 s62, 15
	s_cselect_b32 s14, s16, s14
	s_cmp_gt_u32 s97, 15
	s_cselect_b32 s15, s95, s15
	s_or_b32 s16, s12, 0x10000000
	s_or_b32 s95, s13, 0x10000000
	v_cmp_le_u32_e64 s[8:9], s16, v8
	v_cmp_le_u32_e64 s[2:3], s95, v6
	s_bcnt1_i32_b64 s62, s[8:9]
	s_bcnt1_i32_b64 s97, s[2:3]
	s_cmp_gt_u32 s62, 15
	s_cselect_b32 s12, s16, s12
	s_cmp_gt_u32 s97, 15
	s_cselect_b32 s13, s95, s13
	s_or_b32 s16, s14, 0x10000000
	s_or_b32 s95, s15, 0x10000000
	v_cmp_le_u32_e64 s[8:9], s16, v4
	v_cmp_le_u32_e64 s[2:3], s95, v2
	s_bcnt1_i32_b64 s62, s[8:9]
	s_bcnt1_i32_b64 s97, s[2:3]
	s_cmp_gt_u32 s62, 15
	s_cselect_b32 s14, s16, s14
	s_cmp_gt_u32 s97, 15
	s_cselect_b32 s15, s95, s15
	s_or_b32 s16, s12, 0x8000000
	s_or_b32 s95, s13, 0x8000000
	v_cmp_le_u32_e64 s[8:9], s16, v8
	v_cmp_le_u32_e64 s[2:3], s95, v6
	s_bcnt1_i32_b64 s62, s[8:9]
	s_bcnt1_i32_b64 s97, s[2:3]
	s_cmp_gt_u32 s62, 15
	s_cselect_b32 s12, s16, s12
	s_cmp_gt_u32 s97, 15
	s_cselect_b32 s13, s95, s13
	s_or_b32 s16, s14, 0x8000000
	s_or_b32 s95, s15, 0x8000000
	v_cmp_le_u32_e64 s[8:9], s16, v4
	v_cmp_le_u32_e64 s[2:3], s95, v2
	s_bcnt1_i32_b64 s62, s[8:9]
	s_bcnt1_i32_b64 s97, s[2:3]
	s_cmp_gt_u32 s62, 15
	s_cselect_b32 s14, s16, s14
	s_cmp_gt_u32 s97, 15
	s_cselect_b32 s15, s95, s15
	s_or_b32 s16, s12, 0x4000000
	s_or_b32 s95, s13, 0x4000000
	v_cmp_le_u32_e64 s[8:9], s16, v8
	v_cmp_le_u32_e64 s[2:3], s95, v6
	s_bcnt1_i32_b64 s62, s[8:9]
	s_bcnt1_i32_b64 s97, s[2:3]
	s_cmp_gt_u32 s62, 15
	s_cselect_b32 s12, s16, s12
	s_cmp_gt_u32 s97, 15
	s_cselect_b32 s13, s95, s13
	s_or_b32 s16, s14, 0x4000000
	s_or_b32 s95, s15, 0x4000000
	v_cmp_le_u32_e64 s[8:9], s16, v4
	v_cmp_le_u32_e64 s[2:3], s95, v2
	s_bcnt1_i32_b64 s62, s[8:9]
	s_bcnt1_i32_b64 s97, s[2:3]
	s_cmp_gt_u32 s62, 15
	s_cselect_b32 s14, s16, s14
	s_cmp_gt_u32 s97, 15
	s_cselect_b32 s15, s95, s15
	s_or_b32 s16, s12, 0x2000000
	s_or_b32 s95, s13, 0x2000000
	v_cmp_le_u32_e64 s[8:9], s16, v8
	v_cmp_le_u32_e64 s[2:3], s95, v6
	s_bcnt1_i32_b64 s62, s[8:9]
	s_bcnt1_i32_b64 s97, s[2:3]
	s_cmp_gt_u32 s62, 15
	s_cselect_b32 s12, s16, s12
	s_cmp_gt_u32 s97, 15
	s_cselect_b32 s13, s95, s13
	s_or_b32 s16, s14, 0x2000000
	s_or_b32 s95, s15, 0x2000000
	v_cmp_le_u32_e64 s[8:9], s16, v4
	v_cmp_le_u32_e64 s[2:3], s95, v2
	s_bcnt1_i32_b64 s62, s[8:9]
	s_bcnt1_i32_b64 s97, s[2:3]
	s_cmp_gt_u32 s62, 15
	s_cselect_b32 s14, s16, s14
	s_cmp_gt_u32 s97, 15
	s_cselect_b32 s15, s95, s15
	s_or_b32 s16, s12, 0x1000000
	s_or_b32 s95, s13, 0x1000000
	v_cmp_le_u32_e64 s[8:9], s16, v8
	v_cmp_le_u32_e64 s[2:3], s95, v6
	s_bcnt1_i32_b64 s62, s[8:9]
	s_bcnt1_i32_b64 s97, s[2:3]
	s_cmp_gt_u32 s62, 15
	s_cselect_b32 s12, s16, s12
	s_cmp_gt_u32 s97, 15
	s_cselect_b32 s13, s95, s13
	s_or_b32 s16, s14, 0x1000000
	s_or_b32 s95, s15, 0x1000000
	v_cmp_le_u32_e64 s[8:9], s16, v4
	v_cmp_le_u32_e64 s[2:3], s95, v2
	s_bcnt1_i32_b64 s62, s[8:9]
	s_bcnt1_i32_b64 s97, s[2:3]
	s_cmp_gt_u32 s62, 15
	s_cselect_b32 s14, s16, s14
	s_cmp_gt_u32 s97, 15
	s_cselect_b32 s15, s95, s15
	s_or_b32 s16, s12, 0x800000
	s_or_b32 s95, s13, 0x800000
	v_cmp_le_u32_e64 s[8:9], s16, v8
	v_cmp_le_u32_e64 s[2:3], s95, v6
	s_bcnt1_i32_b64 s62, s[8:9]
	s_bcnt1_i32_b64 s97, s[2:3]
	s_cmp_gt_u32 s62, 15
	s_cselect_b32 s12, s16, s12
	s_cmp_gt_u32 s97, 15
	s_cselect_b32 s13, s95, s13
	s_or_b32 s16, s14, 0x800000
	s_or_b32 s95, s15, 0x800000
	v_cmp_le_u32_e64 s[8:9], s16, v4
	v_cmp_le_u32_e64 s[2:3], s95, v2
	s_bcnt1_i32_b64 s62, s[8:9]
	s_bcnt1_i32_b64 s97, s[2:3]
	s_cmp_gt_u32 s62, 15
	s_cselect_b32 s14, s16, s14
	s_cmp_gt_u32 s97, 15
	s_cselect_b32 s15, s95, s15
	s_or_b32 s16, s12, 0x400000
	s_or_b32 s95, s13, 0x400000
	v_cmp_le_u32_e64 s[8:9], s16, v8
	v_cmp_le_u32_e64 s[2:3], s95, v6
	s_bcnt1_i32_b64 s62, s[8:9]
	s_bcnt1_i32_b64 s97, s[2:3]
	s_cmp_gt_u32 s62, 15
	s_cselect_b32 s12, s16, s12
	s_cmp_gt_u32 s97, 15
	s_cselect_b32 s13, s95, s13
	s_or_b32 s16, s14, 0x400000
	s_or_b32 s95, s15, 0x400000
	v_cmp_le_u32_e64 s[8:9], s16, v4
	v_cmp_le_u32_e64 s[2:3], s95, v2
	s_bcnt1_i32_b64 s62, s[8:9]
	s_bcnt1_i32_b64 s97, s[2:3]
	s_cmp_gt_u32 s62, 15
	s_cselect_b32 s14, s16, s14
	s_cmp_gt_u32 s97, 15
	s_cselect_b32 s15, s95, s15
	s_or_b32 s16, s12, 0x200000
	s_or_b32 s95, s13, 0x200000
	v_cmp_le_u32_e64 s[8:9], s16, v8
	v_cmp_le_u32_e64 s[2:3], s95, v6
	s_bcnt1_i32_b64 s62, s[8:9]
	s_bcnt1_i32_b64 s97, s[2:3]
	s_cmp_gt_u32 s62, 15
	s_cselect_b32 s12, s16, s12
	s_cmp_gt_u32 s97, 15
	s_cselect_b32 s13, s95, s13
	s_or_b32 s16, s14, 0x200000
	s_or_b32 s95, s15, 0x200000
	v_cmp_le_u32_e64 s[8:9], s16, v4
	v_cmp_le_u32_e64 s[2:3], s95, v2
	s_bcnt1_i32_b64 s62, s[8:9]
	s_bcnt1_i32_b64 s97, s[2:3]
	s_cmp_gt_u32 s62, 15
	s_cselect_b32 s14, s16, s14
	s_cmp_gt_u32 s97, 15
	s_cselect_b32 s15, s95, s15
	s_or_b32 s16, s12, 0x100000
	s_or_b32 s95, s13, 0x100000
	v_cmp_le_u32_e64 s[8:9], s16, v8
	v_cmp_le_u32_e64 s[2:3], s95, v6
	s_bcnt1_i32_b64 s62, s[8:9]
	s_bcnt1_i32_b64 s97, s[2:3]
	s_cmp_gt_u32 s62, 15
	s_cselect_b32 s12, s16, s12
	s_cmp_gt_u32 s97, 15
	s_cselect_b32 s13, s95, s13
	s_or_b32 s16, s14, 0x100000
	s_or_b32 s95, s15, 0x100000
	v_cmp_le_u32_e64 s[8:9], s16, v4
	v_cmp_le_u32_e64 s[2:3], s95, v2
	s_bcnt1_i32_b64 s62, s[8:9]
	s_bcnt1_i32_b64 s97, s[2:3]
	s_cmp_gt_u32 s62, 15
	s_cselect_b32 s14, s16, s14
	s_cmp_gt_u32 s97, 15
	s_cselect_b32 s15, s95, s15
	s_or_b32 s16, s12, 0x80000
	s_or_b32 s95, s13, 0x80000
	v_cmp_le_u32_e64 s[8:9], s16, v8
	v_cmp_le_u32_e64 s[2:3], s95, v6
	s_bcnt1_i32_b64 s62, s[8:9]
	s_bcnt1_i32_b64 s97, s[2:3]
	s_cmp_gt_u32 s62, 15
	s_cselect_b32 s12, s16, s12
	s_cmp_gt_u32 s97, 15
	s_cselect_b32 s13, s95, s13
	s_or_b32 s16, s14, 0x80000
	s_or_b32 s95, s15, 0x80000
	v_cmp_le_u32_e64 s[8:9], s16, v4
	v_cmp_le_u32_e64 s[2:3], s95, v2
	s_bcnt1_i32_b64 s62, s[8:9]
	s_bcnt1_i32_b64 s97, s[2:3]
	s_cmp_gt_u32 s62, 15
	s_cselect_b32 s14, s16, s14
	s_cmp_gt_u32 s97, 15
	s_cselect_b32 s15, s95, s15
	s_or_b32 s16, s12, 0x40000
	s_or_b32 s95, s13, 0x40000
	v_cmp_le_u32_e64 s[8:9], s16, v8
	v_cmp_le_u32_e64 s[2:3], s95, v6
	s_bcnt1_i32_b64 s62, s[8:9]
	s_bcnt1_i32_b64 s97, s[2:3]
	s_cmp_gt_u32 s62, 15
	s_cselect_b32 s12, s16, s12
	s_cmp_gt_u32 s97, 15
	s_cselect_b32 s13, s95, s13
	s_or_b32 s16, s14, 0x40000
	s_or_b32 s95, s15, 0x40000
	v_cmp_le_u32_e64 s[8:9], s16, v4
	v_cmp_le_u32_e64 s[2:3], s95, v2
	s_bcnt1_i32_b64 s62, s[8:9]
	s_bcnt1_i32_b64 s97, s[2:3]
	s_cmp_gt_u32 s62, 15
	s_cselect_b32 s14, s16, s14
	s_cmp_gt_u32 s97, 15
	s_cselect_b32 s15, s95, s15
	s_or_b32 s16, s12, 0x20000
	s_or_b32 s95, s13, 0x20000
	v_cmp_le_u32_e64 s[8:9], s16, v8
	v_cmp_le_u32_e64 s[2:3], s95, v6
	s_bcnt1_i32_b64 s62, s[8:9]
	s_bcnt1_i32_b64 s97, s[2:3]
	s_cmp_gt_u32 s62, 15
	s_cselect_b32 s12, s16, s12
	s_cmp_gt_u32 s97, 15
	s_cselect_b32 s13, s95, s13
	s_or_b32 s16, s14, 0x20000
	s_or_b32 s95, s15, 0x20000
	v_cmp_le_u32_e64 s[8:9], s16, v4
	v_cmp_le_u32_e64 s[2:3], s95, v2
	s_bcnt1_i32_b64 s62, s[8:9]
	s_bcnt1_i32_b64 s97, s[2:3]
	s_cmp_gt_u32 s62, 15
	s_cselect_b32 s14, s16, s14
	s_cmp_gt_u32 s97, 15
	s_cselect_b32 s15, s95, s15
	s_or_b32 s16, s12, 0x10000
	s_or_b32 s95, s13, 0x10000
	v_cmp_le_u32_e64 s[8:9], s16, v8
	v_cmp_le_u32_e64 s[2:3], s95, v6
	s_bcnt1_i32_b64 s62, s[8:9]
	s_bcnt1_i32_b64 s97, s[2:3]
	s_cmp_gt_u32 s62, 15
	s_cselect_b32 s12, s16, s12
	s_cmp_gt_u32 s97, 15
	s_cselect_b32 s13, s95, s13
	s_or_b32 s16, s14, 0x10000
	s_or_b32 s95, s15, 0x10000
	v_cmp_le_u32_e64 s[8:9], s16, v4
	v_cmp_le_u32_e64 s[2:3], s95, v2
	s_bcnt1_i32_b64 s62, s[8:9]
	s_bcnt1_i32_b64 s97, s[2:3]
	s_cmp_gt_u32 s62, 15
	s_cselect_b32 s14, s16, s14
	s_cmp_gt_u32 s97, 15
	s_cselect_b32 s15, s95, s15
	s_or_b32 s16, s12, 0x8000
	s_or_b32 s95, s13, 0x8000
	v_cmp_le_u32_e64 s[8:9], s16, v8
	v_cmp_le_u32_e64 s[2:3], s95, v6
	s_bcnt1_i32_b64 s62, s[8:9]
	s_bcnt1_i32_b64 s97, s[2:3]
	s_cmp_gt_u32 s62, 15
	s_cselect_b32 s12, s16, s12
	s_cmp_gt_u32 s97, 15
	s_cselect_b32 s13, s95, s13
	s_or_b32 s16, s14, 0x8000
	s_or_b32 s95, s15, 0x8000
	v_cmp_le_u32_e64 s[8:9], s16, v4
	v_cmp_le_u32_e64 s[2:3], s95, v2
	s_bcnt1_i32_b64 s62, s[8:9]
	s_bcnt1_i32_b64 s97, s[2:3]
	s_cmp_gt_u32 s62, 15
	s_cselect_b32 s14, s16, s14
	s_cmp_gt_u32 s97, 15
	s_cselect_b32 s15, s95, s15
	s_or_b32 s16, s12, 0x4000
	s_or_b32 s95, s13, 0x4000
	v_cmp_le_u32_e64 s[8:9], s16, v8
	v_cmp_le_u32_e64 s[2:3], s95, v6
	s_bcnt1_i32_b64 s62, s[8:9]
	s_bcnt1_i32_b64 s97, s[2:3]
	s_cmp_gt_u32 s62, 15
	s_cselect_b32 s12, s16, s12
	s_cmp_gt_u32 s97, 15
	s_cselect_b32 s13, s95, s13
	s_or_b32 s16, s14, 0x4000
	s_or_b32 s95, s15, 0x4000
	v_cmp_le_u32_e64 s[8:9], s16, v4
	v_cmp_le_u32_e64 s[2:3], s95, v2
	s_bcnt1_i32_b64 s62, s[8:9]
	s_bcnt1_i32_b64 s97, s[2:3]
	s_cmp_gt_u32 s62, 15
	s_cselect_b32 s14, s16, s14
	s_cmp_gt_u32 s97, 15
	s_cselect_b32 s15, s95, s15
	s_or_b32 s16, s12, 0x2000
	s_or_b32 s95, s13, 0x2000
	v_cmp_le_u32_e64 s[8:9], s16, v8
	v_cmp_le_u32_e64 s[2:3], s95, v6
	s_bcnt1_i32_b64 s62, s[8:9]
	s_bcnt1_i32_b64 s97, s[2:3]
	s_cmp_gt_u32 s62, 15
	s_cselect_b32 s12, s16, s12
	s_cmp_gt_u32 s97, 15
	s_cselect_b32 s13, s95, s13
	s_or_b32 s16, s14, 0x2000
	s_or_b32 s95, s15, 0x2000
	v_cmp_le_u32_e64 s[8:9], s16, v4
	v_cmp_le_u32_e64 s[2:3], s95, v2
	s_bcnt1_i32_b64 s62, s[8:9]
	s_bcnt1_i32_b64 s97, s[2:3]
	s_cmp_gt_u32 s62, 15
	s_cselect_b32 s14, s16, s14
	s_cmp_gt_u32 s97, 15
	s_cselect_b32 s15, s95, s15
	s_or_b32 s16, s12, 0x1000
	s_or_b32 s95, s13, 0x1000
	v_cmp_le_u32_e64 s[8:9], s16, v8
	v_cmp_le_u32_e64 s[2:3], s95, v6
	s_bcnt1_i32_b64 s62, s[8:9]
	s_bcnt1_i32_b64 s97, s[2:3]
	s_cmp_gt_u32 s62, 15
	s_cselect_b32 s12, s16, s12
	s_cmp_gt_u32 s97, 15
	s_cselect_b32 s13, s95, s13
	s_or_b32 s16, s14, 0x1000
	s_or_b32 s95, s15, 0x1000
	v_cmp_le_u32_e64 s[8:9], s16, v4
	v_cmp_le_u32_e64 s[2:3], s95, v2
	s_bcnt1_i32_b64 s62, s[8:9]
	s_bcnt1_i32_b64 s97, s[2:3]
	s_cmp_gt_u32 s62, 15
	s_cselect_b32 s14, s16, s14
	s_cmp_gt_u32 s97, 15
	s_cselect_b32 s15, s95, s15
	s_or_b32 s16, s12, 0x800
	s_or_b32 s95, s13, 0x800
	v_cmp_le_u32_e64 s[8:9], s16, v8
	v_cmp_le_u32_e64 s[2:3], s95, v6
	s_bcnt1_i32_b64 s62, s[8:9]
	s_bcnt1_i32_b64 s97, s[2:3]
	s_cmp_gt_u32 s62, 15
	s_cselect_b32 s12, s16, s12
	s_cmp_gt_u32 s97, 15
	s_cselect_b32 s13, s95, s13
	s_or_b32 s16, s14, 0x800
	s_or_b32 s95, s15, 0x800
	v_cmp_le_u32_e64 s[8:9], s16, v4
	v_cmp_le_u32_e64 s[2:3], s95, v2
	s_bcnt1_i32_b64 s62, s[8:9]
	s_bcnt1_i32_b64 s97, s[2:3]
	s_cmp_gt_u32 s62, 15
	s_cselect_b32 s14, s16, s14
	s_cmp_gt_u32 s97, 15
	s_cselect_b32 s15, s95, s15
	s_or_b32 s16, s12, 0x400
	s_or_b32 s95, s13, 0x400
	v_cmp_le_u32_e64 s[8:9], s16, v8
	v_cmp_le_u32_e64 s[2:3], s95, v6
	s_bcnt1_i32_b64 s62, s[8:9]
	s_bcnt1_i32_b64 s97, s[2:3]
	s_cmp_gt_u32 s62, 15
	s_cselect_b32 s12, s16, s12
	s_cmp_gt_u32 s97, 15
	s_cselect_b32 s13, s95, s13
	s_or_b32 s16, s14, 0x400
	s_or_b32 s95, s15, 0x400
	v_cmp_le_u32_e64 s[8:9], s16, v4
	v_cmp_le_u32_e64 s[2:3], s95, v2
	s_bcnt1_i32_b64 s62, s[8:9]
	s_bcnt1_i32_b64 s97, s[2:3]
	s_cmp_gt_u32 s62, 15
	s_cselect_b32 s14, s16, s14
	s_cmp_gt_u32 s97, 15
	s_cselect_b32 s15, s95, s15
	s_or_b32 s16, s12, 0x200
	s_or_b32 s95, s13, 0x200
	v_cmp_le_u32_e64 s[8:9], s16, v8
	v_cmp_le_u32_e64 s[2:3], s95, v6
	s_bcnt1_i32_b64 s62, s[8:9]
	s_bcnt1_i32_b64 s97, s[2:3]
	s_cmp_gt_u32 s62, 15
	s_cselect_b32 s12, s16, s12
	s_cmp_gt_u32 s97, 15
	s_cselect_b32 s13, s95, s13
	s_or_b32 s16, s14, 0x200
	s_or_b32 s95, s15, 0x200
	v_cmp_le_u32_e64 s[8:9], s16, v4
	v_cmp_le_u32_e64 s[2:3], s95, v2
	s_bcnt1_i32_b64 s62, s[8:9]
	s_bcnt1_i32_b64 s97, s[2:3]
	s_cmp_gt_u32 s62, 15
	s_cselect_b32 s14, s16, s14
	s_cmp_gt_u32 s97, 15
	s_cselect_b32 s15, s95, s15
	s_or_b32 s16, s12, 0x100
	s_or_b32 s95, s13, 0x100
	v_cmp_le_u32_e64 s[8:9], s16, v8
	v_cmp_le_u32_e64 s[2:3], s95, v6
	s_bcnt1_i32_b64 s62, s[8:9]
	s_bcnt1_i32_b64 s97, s[2:3]
	s_cmp_gt_u32 s62, 15
	s_cselect_b32 s12, s16, s12
	s_cmp_gt_u32 s97, 15
	s_cselect_b32 s13, s95, s13
	s_or_b32 s16, s14, 0x100
	s_or_b32 s95, s15, 0x100
	v_cmp_le_u32_e64 s[8:9], s16, v4
	v_cmp_le_u32_e64 s[2:3], s95, v2
	s_bcnt1_i32_b64 s62, s[8:9]
	s_bcnt1_i32_b64 s97, s[2:3]
	s_cmp_gt_u32 s62, 15
	s_cselect_b32 s14, s16, s14
	s_cmp_gt_u32 s97, 15
	s_cselect_b32 s15, s95, s15
	s_or_b32 s16, s12, 0x80
	s_or_b32 s95, s13, 0x80
	v_cmp_le_u32_e64 s[8:9], s16, v8
	v_cmp_le_u32_e64 s[2:3], s95, v6
	s_bcnt1_i32_b64 s62, s[8:9]
	s_bcnt1_i32_b64 s97, s[2:3]
	s_cmp_gt_u32 s62, 15
	s_cselect_b32 s12, s16, s12
	s_cmp_gt_u32 s97, 15
	s_cselect_b32 s13, s95, s13
	s_or_b32 s16, s14, 0x80
	s_or_b32 s95, s15, 0x80
	v_cmp_le_u32_e64 s[8:9], s16, v4
	v_cmp_le_u32_e64 s[2:3], s95, v2
	s_bcnt1_i32_b64 s62, s[8:9]
	s_bcnt1_i32_b64 s97, s[2:3]
	s_cmp_gt_u32 s62, 15
	s_cselect_b32 s14, s16, s14
	s_cmp_gt_u32 s97, 15
	s_cselect_b32 s15, s95, s15
	s_or_b32 s16, s12, 0x40
	s_or_b32 s95, s13, 0x40
	v_cmp_le_u32_e64 s[8:9], s16, v8
	v_cmp_le_u32_e64 s[2:3], s95, v6
	s_bcnt1_i32_b64 s62, s[8:9]
	s_bcnt1_i32_b64 s97, s[2:3]
	s_cmp_gt_u32 s62, 15
	s_cselect_b32 s12, s16, s12
	s_cmp_gt_u32 s97, 15
	s_cselect_b32 s13, s95, s13
	s_or_b32 s16, s14, 0x40
	s_or_b32 s95, s15, 0x40
	v_cmp_le_u32_e64 s[8:9], s16, v4
	v_cmp_le_u32_e64 s[2:3], s95, v2
	s_bcnt1_i32_b64 s62, s[8:9]
	s_bcnt1_i32_b64 s97, s[2:3]
	s_cmp_gt_u32 s62, 15
	s_cselect_b32 s14, s16, s14
	s_cmp_gt_u32 s97, 15
	s_cselect_b32 s15, s95, s15
	s_or_b32 s16, s12, 32
	s_or_b32 s95, s13, 32
	v_cmp_le_u32_e64 s[8:9], s16, v8
	v_cmp_le_u32_e64 s[2:3], s95, v6
	s_bcnt1_i32_b64 s62, s[8:9]
	s_bcnt1_i32_b64 s97, s[2:3]
	s_cmp_gt_u32 s62, 15
	s_cselect_b32 s12, s16, s12
	s_cmp_gt_u32 s97, 15
	s_cselect_b32 s13, s95, s13
	s_or_b32 s16, s14, 32
	s_or_b32 s95, s15, 32
	v_cmp_le_u32_e64 s[8:9], s16, v4
	v_cmp_le_u32_e64 s[2:3], s95, v2
	s_bcnt1_i32_b64 s62, s[8:9]
	s_bcnt1_i32_b64 s97, s[2:3]
	s_cmp_gt_u32 s62, 15
	s_cselect_b32 s14, s16, s14
	s_cmp_gt_u32 s97, 15
	s_cselect_b32 s15, s95, s15
	s_or_b32 s16, s12, 16
	s_or_b32 s95, s13, 16
	v_cmp_le_u32_e64 s[8:9], s16, v8
	v_cmp_le_u32_e64 s[2:3], s95, v6
	s_bcnt1_i32_b64 s62, s[8:9]
	s_bcnt1_i32_b64 s97, s[2:3]
	s_cmp_gt_u32 s62, 15
	s_cselect_b32 s12, s16, s12
	s_cmp_gt_u32 s97, 15
	s_cselect_b32 s13, s95, s13
	s_or_b32 s16, s14, 16
	s_or_b32 s95, s15, 16
	v_cmp_le_u32_e64 s[8:9], s16, v4
	v_cmp_le_u32_e64 s[2:3], s95, v2
	s_bcnt1_i32_b64 s62, s[8:9]
	s_bcnt1_i32_b64 s97, s[2:3]
	s_cmp_gt_u32 s62, 15
	s_cselect_b32 s14, s16, s14
	s_cmp_gt_u32 s97, 15
	s_cselect_b32 s15, s95, s15
	s_or_b32 s16, s12, 8
	s_or_b32 s95, s13, 8
	v_cmp_le_u32_e64 s[8:9], s16, v8
	v_cmp_le_u32_e64 s[2:3], s95, v6
	s_bcnt1_i32_b64 s62, s[8:9]
	s_bcnt1_i32_b64 s97, s[2:3]
	s_cmp_gt_u32 s62, 15
	s_cselect_b32 s12, s16, s12
	s_cmp_gt_u32 s97, 15
	s_cselect_b32 s13, s95, s13
	s_or_b32 s16, s14, 8
	s_or_b32 s95, s15, 8
	v_cmp_le_u32_e64 s[8:9], s16, v4
	v_cmp_le_u32_e64 s[2:3], s95, v2
	s_bcnt1_i32_b64 s62, s[8:9]
	s_bcnt1_i32_b64 s97, s[2:3]
	s_cmp_gt_u32 s62, 15
	s_cselect_b32 s14, s16, s14
	s_cmp_gt_u32 s97, 15
	s_cselect_b32 s15, s95, s15
	s_or_b32 s16, s12, 4
	s_or_b32 s95, s13, 4
	v_cmp_le_u32_e64 s[8:9], s16, v8
	v_cmp_le_u32_e64 s[2:3], s95, v6
	s_bcnt1_i32_b64 s62, s[8:9]
	s_bcnt1_i32_b64 s97, s[2:3]
	s_cmp_gt_u32 s62, 15
	s_cselect_b32 s12, s16, s12
	s_cmp_gt_u32 s97, 15
	s_cselect_b32 s13, s95, s13
	s_or_b32 s16, s14, 4
	s_or_b32 s95, s15, 4
	v_cmp_le_u32_e64 s[8:9], s16, v4
	v_cmp_le_u32_e64 s[2:3], s95, v2
	s_bcnt1_i32_b64 s62, s[8:9]
	s_bcnt1_i32_b64 s97, s[2:3]
	s_cmp_gt_u32 s62, 15
	s_cselect_b32 s14, s16, s14
	s_cmp_gt_u32 s97, 15
	s_cselect_b32 s15, s95, s15
	s_or_b32 s16, s12, 2
	v_cmp_le_u32_e64 s[8:9], s16, v8
	s_bcnt1_i32_b64 s62, s[8:9]
	s_cmp_gt_u32 s62, 15
	s_nop 0
	s_cselect_b32 s12, s16, s12
	s_or_b32 s16, s13, 2
	v_cmp_le_u32_e64 s[8:9], s16, v6
	s_bcnt1_i32_b64 s62, s[8:9]
	s_cmp_gt_u32 s62, 15
	s_nop 0
	s_cselect_b32 s29, s16, s13
	s_or_b32 s13, s14, 2
	v_cmp_le_u32_e64 s[8:9], s13, v4
	s_bcnt1_i32_b64 s62, s[8:9]
	s_cmp_gt_u32 s62, 15
	s_nop 0
	s_cselect_b32 s27, s13, s14
	s_or_b32 s13, s15, 2
	v_cmp_le_u32_e64 s[8:9], s13, v2
	s_bcnt1_i32_b64 s62, s[8:9]
	s_cmp_gt_u32 s62, 15
	s_nop 0
	s_cselect_b32 s3, s13, s15
	s_or_b32 s2, s12, 1
	v_cmp_le_u32_e64 s[8:9], s2, v8
	s_bcnt1_i32_b64 s62, s[8:9]
	s_cmp_gt_u32 s62, 15
	s_nop 0
	s_cselect_b32 s20, s2, s12
	v_cmp_lt_u32_e64 s[16:17], s20, v8
	v_cmp_eq_u32_e64 s[20:21], s20, v8
	s_bcnt1_i32_b64 s22, s[16:17]
	s_sub_i32 s22, 16, s22
	v_and_b32_e32 v9, s20, v186
	v_and_b32_e32 v8, s21, v167
	v_bcnt_u32_b32 v9, v9, 0
	v_bcnt_u32_b32 v8, v8, v9
	v_cmp_gt_i32_e64 s[22:23], s22, v8
	s_and_b64 s[20:21], s[20:21], s[22:23]
	s_or_b64 s[20:21], s[16:17], s[20:21]
	v_cmp_lt_f32_e64 s[16:17], s88, v7
	s_and_b64 s[16:17], s[20:21], s[16:17]
	s_or_b32 s30, s29, 1
	s_or_b32 s28, s27, 1
	s_or_b32 s26, s3, 1
	v_cndmask_b32_e64 v7, 0, 1, s[16:17]
	v_cmp_le_u32_e64 s[14:15], s30, v6
	v_cmp_le_u32_e64 s[12:13], s28, v4
	v_cmp_le_u32_e64 s[8:9], s26, v2
	s_add_i32 s2, s25, 0
	v_cmp_ne_u32_e64 s[20:21], 0, v7
	s_and_saveexec_b64 s[16:17], s[6:7]
	s_add_i32 s22, s2, 0x10800
	v_mov_b32_e32 v7, s22
	v_mov_b64_e32 v[8:9], s[20:21]
	ds_write_b64 v7, v[8:9]
	s_or_b64 exec, exec, s[16:17]
	s_bcnt1_i32_b64 s62, s[14:15]
	s_cmp_gt_u32 s62, 15
	s_nop 0
	s_cselect_b32 s16, s30, s29
	v_cmp_lt_u32_e64 s[14:15], s16, v6
	v_cmp_eq_u32_e64 s[16:17], s16, v6
	s_bcnt1_i32_b64 s20, s[14:15]
	s_sub_i32 s20, 16, s20
	v_and_b32_e32 v7, s16, v186
	v_and_b32_e32 v6, s17, v167
	v_bcnt_u32_b32 v7, v7, 0
	v_bcnt_u32_b32 v6, v6, v7
	v_cmp_gt_i32_e64 s[20:21], s20, v6
	s_and_b64 s[16:17], s[16:17], s[20:21]
	s_or_b64 s[16:17], s[14:15], s[16:17]
	v_cmp_lt_f32_e64 s[14:15], s88, v5
	s_and_b64 s[14:15], s[16:17], s[14:15]
	s_nop 0
	v_cndmask_b32_e64 v5, 0, 1, s[14:15]
	v_cmp_ne_u32_e64 s[16:17], 0, v5
	s_and_saveexec_b64 s[14:15], s[6:7]
	s_add_i32 s20, s2, 0x10808
	v_mov_b32_e32 v5, s20
	v_mov_b64_e32 v[6:7], s[16:17]
	ds_write_b64 v5, v[6:7]
	s_or_b64 exec, exec, s[14:15]
	s_bcnt1_i32_b64 s62, s[12:13]
	s_cmp_gt_u32 s62, 15
	s_nop 0
	s_cselect_b32 s14, s28, s27
	v_cmp_lt_u32_e64 s[12:13], s14, v4
	v_cmp_eq_u32_e64 s[14:15], s14, v4
	s_bcnt1_i32_b64 s16, s[12:13]
	s_sub_i32 s16, 16, s16
	v_and_b32_e32 v5, s14, v186
	v_and_b32_e32 v4, s15, v167
	v_bcnt_u32_b32 v5, v5, 0
	v_bcnt_u32_b32 v4, v4, v5
	v_cmp_gt_i32_e64 s[16:17], s16, v4
	s_and_b64 s[14:15], s[14:15], s[16:17]
	s_or_b64 s[14:15], s[12:13], s[14:15]
	v_cmp_lt_f32_e64 s[12:13], s88, v3
	s_and_b64 s[12:13], s[14:15], s[12:13]
	s_nop 0
	v_cndmask_b32_e64 v3, 0, 1, s[12:13]
	v_cmp_ne_u32_e64 s[14:15], 0, v3
	s_and_saveexec_b64 s[12:13], s[6:7]
	s_add_i32 s16, s2, 0x10810
	v_mov_b32_e32 v3, s16
	v_mov_b64_e32 v[4:5], s[14:15]
	ds_write_b64 v3, v[4:5]
	s_or_b64 exec, exec, s[12:13]
	s_bcnt1_i32_b64 s62, s[8:9]
	s_cmp_gt_u32 s62, 15
	s_nop 0
	s_cselect_b32 s3, s26, s3
	v_cmp_eq_u32_e64 s[12:13], s3, v2
	v_cmp_lt_u32_e64 s[8:9], s3, v2
	s_bcnt1_i32_b64 s3, s[8:9]
	v_and_b32_e32 v3, s12, v186
	v_and_b32_e32 v2, s13, v167
	v_bcnt_u32_b32 v3, v3, 0
	s_sub_i32 s3, 16, s3
	v_bcnt_u32_b32 v2, v2, v3
	v_cmp_gt_i32_e64 s[14:15], s3, v2
	s_and_b64 s[12:13], s[12:13], s[14:15]
	s_or_b64 s[12:13], s[8:9], s[12:13]
	v_cmp_lt_f32_e64 s[8:9], s88, v1
	s_and_b64 s[8:9], s[12:13], s[8:9]
	s_nop 0
	v_cndmask_b32_e64 v1, 0, 1, s[8:9]
	v_cmp_ne_u32_e64 s[12:13], 0, v1
	s_and_saveexec_b64 s[8:9], s[6:7]
	s_cbranch_execz .LBB0_798
	s_add_i32 s2, s2, 0x10818
	v_mov_b32_e32 v1, s2
	v_mov_b64_e32 v[2:3], s[12:13]
	ds_write_b64 v1, v[2:3]
	s_branch .LBB0_798
